# scan: loader/consumer LDS-DMA with per-image hand-off; prep step-1: g/beta loads first with counted waits, K fragments of tile rows 2-3 requested together
# baseline (speedup 1.0000x reference)
; __device__ __forceinline__ void phase_prep(const Args& a, PG8_LAS unsigned char* lds) {
;     ...
;         bf16x8 ak[4], aq[4], bkf[2][4];
; #pragma unroll
;         for (int s = 0; s < 4; ++s) { ak[s] = *(const bf16x8*)(kbase + (size_t)(16 * lw + r) * 512 + 32 * s + 8 * q); aq[s] = *(const bf16x8*)(qbase + (size_t)(16 * lw + r) * 512 + 32 * s + 8 * q); }
; #pragma unroll
;         for (int tj = 0; tj < 2; ++tj)
; #pragma unroll
;             for (int s = 0; s < 4; ++s) bkf[tj][s] = *(const bf16x8*)(kbase + (size_t)(16 * tj + r) * 512 + 32 * s + 8 * q);
;         bf16x8 pv[2][2], pk[2][2];
;         if (role != 0) {
; #pragma unroll
;         for (int cc = 0; cc < 2; ++cc) { const int ct = 2 * lw + cc;
;             pv[cc][0] = *(const bf16x8*)(vTb + (size_t)(16 * ct + r) * 64 + 8 * q); pv[cc][1] = *(const bf16x8*)(vTb + (size_t)(16 * ct + r) * 64 + 32 + 8 * q);
;             pk[cc][0] = *(const bf16x8*)(kTb + (size_t)(16 * ct + r) * 64 + 8 * q); pk[cc][1] = *(const bf16x8*)(kTb + (size_t)(16 * ct + r) * 64 + 32 + 8 * q); } }
;         float gv = gB[(r0 + lane) * 4 + h];
; #pragma unroll
;         for (int off = 1; off < 64; off <<= 1) { const float t = __shfl_up(gv, off); if (lane >= off) gv += t; }
;         const float g63 = __shfl(gv, 63);
;         if (lw == 0) { sG[lane] = gv; sB[lane] = betaB[(r0 + lane) * 4 + h]; sE[lane] = __expf(gv); sK[lane] = __expf(g63 - gv); }
;         if ((tid & 255) == 0) glast[item] = __expf(g63);
.LBB0_253:
	s_ashr_i32 s18, s38, 1
	s_lshl_b32 s14, s38, 1
	s_and_b32 s14, s14, 2
	s_ashr_i32 s19, s18, 31
	s_add_i32 s26, s14, s33
	s_lshl_b64 s[20:21], s[18:19], 15
	s_lshl_b64 s[24:25], s[18:19], 16
	v_readlane_b32 s14, v253, 43
	s_add_u32 s22, s14, s24
	v_readlane_b32 s14, v253, 44
	s_addc_u32 s23, s14, s25
	s_lshl_b32 s14, s26, 7
	s_lshl_b32 s27, s26, 8
	s_add_u32 s22, s22, s27
	s_addc_u32 s23, s23, 0
	v_readlane_b32 s39, v253, 45
	s_add_u32 s39, s39, s24
	v_readlane_b32 s40, v253, 46
	s_addc_u32 s40, s40, s25
	s_add_u32 vcc_lo, s39, s27
	s_addc_u32 vcc_hi, s40, 0
	v_mov_b32_e32 v107, v97
	v_lshl_add_u64 v[32:33], vcc, 0, v[106:107]
	v_lshl_add_u64 v[34:35], s[22:23], 0, v[106:107]
	v_lshl_add_u64 v[32:33], v[32:33], 0, v[96:97]
	v_lshl_add_u64 v[36:37], v[34:35], 0, v[96:97]
	s_lshl_b64 s[100:101], s[18:19], 8
	v_mov_b32_e32 v129, s101
	v_or_b32_e32 v128, s100, v98
	s_mov_b32 s100, s26
	s_mov_b32 s101, s15
	v_lshl_add_u64 v[128:129], v[128:129], 0, s[100:101]
	v_lshl_add_u64 v[230:231], v[128:129], 2, s[8:9]
	global_load_dword v234, v[230:231], off
	v_readlane_b32 s100, v253, 49
	v_readlane_b32 s101, v253, 50
	s_nop 1
	v_lshl_add_u64 v[232:233], v[128:129], 2, s[100:101]
	global_load_dword v111, v[232:233], off
	global_load_dwordx4 v[56:59], v[32:33], off
	global_load_dwordx4 v[48:51], v[32:33], off offset:64
	global_load_dwordx4 v[60:63], v[36:37], off
	global_load_dwordx4 v[52:55], v[36:37], off offset:64
	global_load_dwordx4 v[40:43], v[32:33], off offset:128
	s_nop 0
	global_load_dwordx4 v[32:35], v[32:33], off offset:192
	s_nop 0
	global_load_dwordx4 v[44:47], v[36:37], off offset:128
	s_nop 0
	global_load_dwordx4 v[36:39], v[36:37], off offset:192
	v_lshl_add_u64 v[64:65], vcc, 0, v[96:97]
	v_mov_b32_e32 v109, v97
	v_lshl_add_u64 v[126:127], v[64:65], 0, v[108:109]
	s_movk_i32 s22, 0x4000
	v_add_co_u32_e32 v64, vcc, s22, v126
	global_load_dwordx4 v[92:95], v[126:127], off
	global_load_dwordx4 v[88:91], v[126:127], off offset:64
	global_load_dwordx4 v[84:87], v[126:127], off offset:128
	global_load_dwordx4 v[80:83], v[126:127], off offset:192
	v_addc_co_u32_e32 v65, vcc, 0, v127, vcc
	global_load_dwordx4 v[76:79], v[64:65], off
	global_load_dwordx4 v[72:75], v[64:65], off offset:64
	global_load_dwordx4 v[68:71], v[64:65], off offset:128
	s_nop 0
	global_load_dwordx4 v[64:67], v[64:65], off offset:192
	s_lshl_b64 s[22:23], s[14:15], 6
	s_add_u32 s20, s22, s20
	s_addc_u32 s21, s23, s21
	s_lshl_b64 s[22:23], s[20:21], 1
	s_add_u32 s20, s10, s22
	s_addc_u32 s21, s11, s23
	v_readlane_b32 s14, v253, 47
	v_readlane_b32 s40, v253, 53
	s_add_u32 s22, s14, s22
	v_readlane_b32 s14, v253, 48
	v_readlane_b32 s41, v253, 54
	s_addc_u32 s23, s14, s23
	s_waitcnt vmcnt(16)
	s_andn2_b64 vcc, exec, s[40:41]
	s_cbranch_vccnz .LBB0_255
	v_mov_b32_e32 v115, v97
	v_lshl_add_u64 v[0:1], s[22:23], 0, v[114:115]
	v_lshl_add_u64 v[8:9], s[20:21], 0, v[114:115]
	v_lshl_add_u64 v[16:17], v[0:1], 0, v[96:97]
	v_lshl_add_u64 v[24:25], v[8:9], 0, v[96:97]
	global_load_dwordx4 v[0:3], v[16:17], off
	global_load_dwordx4 v[4:7], v[16:17], off offset:64
	global_load_dwordx4 v[8:11], v[24:25], off
	global_load_dwordx4 v[12:15], v[24:25], off offset:64
	global_load_dwordx4 v[20:23], v[16:17], off offset:2048
	global_load_dwordx4 v[28:31], v[16:17], off offset:2112
	s_nop 0
	global_load_dwordx4 v[16:19], v[24:25], off offset:2048
	s_nop 0
	global_load_dwordx4 v[24:27], v[24:25], off offset:2112

	.amdhsa_kernel _Z4mega4Args
		.amdhsa_group_segment_fixed_size 19456
		.amdhsa_private_segment_fixed_size 0
		.amdhsa_kernarg_size 416
		.amdhsa_user_sgpr_count 2
		.amdhsa_user_sgpr_dispatch_ptr 0
		.amdhsa_user_sgpr_queue_ptr 0
		.amdhsa_user_sgpr_kernarg_segment_ptr 1
		.amdhsa_user_sgpr_dispatch_id 0
		.amdhsa_user_sgpr_kernarg_preload_length 0
		.amdhsa_user_sgpr_kernarg_preload_offset 0
		.amdhsa_user_sgpr_private_segment_size 0
		.amdhsa_uses_dynamic_stack 0
		.amdhsa_enable_private_segment 0
		.amdhsa_system_sgpr_workgroup_id_x 1
		.amdhsa_system_sgpr_workgroup_id_y 0
		.amdhsa_system_sgpr_workgroup_id_z 0
		.amdhsa_system_sgpr_workgroup_info 0
		.amdhsa_system_vgpr_workitem_id 2
		.amdhsa_next_free_vgpr 254
		.amdhsa_next_free_sgpr 102
		.amdhsa_accum_offset 256
		.amdhsa_reserve_vcc 1
		.amdhsa_float_round_mode_32 0
		.amdhsa_float_round_mode_16_64 0
		.amdhsa_float_denorm_mode_32 3
		.amdhsa_float_denorm_mode_16_64 3
		.amdhsa_dx10_clamp 1
		.amdhsa_ieee_mode 1
		.amdhsa_fp16_overflow 0
		.amdhsa_tg_split 0
		.amdhsa_exception_fp_ieee_invalid_op 0
		.amdhsa_exception_fp_denorm_src 0
		.amdhsa_exception_fp_ieee_div_zero 0
		.amdhsa_exception_fp_ieee_overflow 0
		.amdhsa_exception_fp_ieee_underflow 0
		.amdhsa_exception_fp_ieee_inexact 0
		.amdhsa_exception_int_div_zero 0
	.end_amdhsa_kernel

; __global__ void __launch_bounds__(NT) mega(Args a) {
;     extern __shared__ __attribute__((aligned(16))) unsigned char lds_raw[];
amdhsa.kernels:
  - .agpr_count:     0
    .args:
      - .offset:         0
        .size:           160
        .value_kind:     by_value
      - .offset:         160
        .size:           4
        .value_kind:     hidden_block_count_x
      - .offset:         164
        .size:           4
        .value_kind:     hidden_block_count_y
      - .offset:         168
        .size:           4
        .value_kind:     hidden_block_count_z
      - .offset:         172
        .size:           2
        .value_kind:     hidden_group_size_x
      - .offset:         174
        .size:           2
        .value_kind:     hidden_group_size_y
      - .offset:         176
        .size:           2
        .value_kind:     hidden_group_size_z
      - .offset:         178
        .size:           2
        .value_kind:     hidden_remainder_x
      - .offset:         180
        .size:           2
        .value_kind:     hidden_remainder_y
      - .offset:         182
        .size:           2
        .value_kind:     hidden_remainder_z
      - .offset:         200
        .size:           8
        .value_kind:     hidden_global_offset_x
      - .offset:         208
        .size:           8
        .value_kind:     hidden_global_offset_y
      - .offset:         216
        .size:           8
        .value_kind:     hidden_global_offset_z
      - .offset:         224
        .size:           2
        .value_kind:     hidden_grid_dims
      - .offset:         248
        .size:           8
        .value_kind:     hidden_multigrid_sync_arg
      - .offset:         280
        .size:           4
        .value_kind:     hidden_dynamic_lds_size
    .group_segment_fixed_size: 19456
    .kernarg_segment_align: 8
    .kernarg_segment_size: 416
    .language:       OpenCL C
    .language_version:
      - 2
      - 0
    .max_flat_workgroup_size: 512
    .name:           _Z4mega4Args
    .private_segment_fixed_size: 0
    .sgpr_count:     108
    .sgpr_spill_count: 98
    .symbol:         _Z4mega4Args.kd
    .uniform_work_group_size: 1
    .uses_dynamic_stack: false
    .vgpr_count:     254
    .vgpr_spill_count: 0
    .wavefront_size: 64
